# attention: XCD-aware item swizzle (32 consecutive items per XCD per 256-block) so neighbouring items share K/V chunks in one L2
# speedup vs baseline: 1.0028x; 1.0024x over previous
.LBB0_254:
	v_writelane_b32 v254, s56, 63
	v_readfirstlane_b32 s2, v154
	v_readlane_b32 s0, v254, 58
	v_readlane_b32 s1, v254, 59
	s_and_b64 s[0:1], s[0:1], exec
	s_movk_i32 s0, 0x618
	s_cselect_b32 s6, s0, 0x600
	s_cmp_ge_i32 s84, s6
	v_writelane_b32 v252, s57, 0
	s_cbranch_scc1 .LBB0_352
	v_or_b32_e32 v3, v38, v37
	v_bfe_u32 v5, v154, 1, 1
	v_lshrrev_b32_e32 v4, 1, v154
	v_or_b32_e32 v10, v3, v5
	v_lshlrev_b32_e32 v163, 4, v10
	v_bitop3_b32 v10, v3, v4, 1 bitop3:0x72
	v_lshlrev_b32_e32 v164, 4, v10
	v_or_b32_e32 v10, 2, v5
	v_bitop3_b32 v11, v38, v10, v37 bitop3:0x36
	v_bitop3_b32 v10, v3, v10, 1 bitop3:0x36
	v_lshlrev_b32_e32 v166, 4, v10
	v_or_b32_e32 v10, 4, v5
	v_lshlrev_b32_e32 v165, 4, v11
	v_bitop3_b32 v11, v38, v10, v37 bitop3:0x36
	v_bitop3_b32 v10, v3, v10, 1 bitop3:0x36
	v_lshlrev_b32_e32 v168, 4, v10
	v_or_b32_e32 v10, 6, v5
	v_lshlrev_b32_e32 v2, 1, v140
	v_lshlrev_b32_e32 v167, 4, v11
	v_bitop3_b32 v11, v38, v10, v37 bitop3:0x36
	v_bitop3_b32 v10, v3, v10, 1 bitop3:0x36
	v_lshrrev_b32_e32 v0, 4, v154
	v_and_or_b32 v2, v2, 24, v39
	v_lshlrev_b32_e32 v170, 4, v10
	v_or_b32_e32 v10, 8, v5
	v_bfe_u32 v148, v154, 4, 2
	v_lshlrev_b32_e32 v149, 8, v2
	v_bitop3_b32 v2, v0, v140, 3 bitop3:0x6c
	v_readlane_b32 s0, v254, 58
	v_lshlrev_b32_e32 v169, 4, v11
	v_bitop3_b32 v11, v38, v10, v37 bitop3:0x36
	v_bitop3_b32 v10, v3, v10, 1 bitop3:0x36
	v_lshlrev_b32_e32 v150, 4, v2
	v_bitop3_b32 v2, v148, v140, 4 bitop3:0x36
	v_readlane_b32 s1, v254, 59
	v_lshlrev_b32_e32 v172, 4, v10
	v_or_b32_e32 v10, 10, v5
	v_lshlrev_b32_e32 v152, 4, v2
	v_bitop3_b32 v2, v148, v140, 8 bitop3:0x36
	s_and_b64 s[0:1], s[0:1], exec
	v_lshlrev_b32_e32 v171, 4, v11
	v_bitop3_b32 v11, v38, v10, v37 bitop3:0x36
	v_bitop3_b32 v10, v3, v10, 1 bitop3:0x36
	v_lshlrev_b32_e32 v156, 4, v2
	v_bitop3_b32 v2, v148, v140, 12 bitop3:0x36
	s_cselect_b32 s7, 0, 8
	s_cselect_b32 s29, 0, 4
	v_lshlrev_b32_e32 v174, 4, v10
	v_or_b32_e32 v10, 12, v5
	v_or_b32_e32 v5, 14, v5
	v_bfe_u32 v13, v0, 1, 1
	v_bitop3_b32 v0, v0, v154, 3 bitop3:0x6c
	s_ashr_i32 s3, s2, 6
	v_max_i32_e32 v29, 0xffffffd1, v154
	v_lshlrev_b32_e32 v158, 4, v2
	v_lshlrev_b32_e32 v2, 6, v140
	v_lshrrev_b32_e32 v6, 1, v142
	v_lshrrev_b32_e32 v9, 1, v143
	v_lshlrev_b32_e32 v173, 4, v11
	v_bitop3_b32 v11, v38, v10, v37 bitop3:0x36
	v_bitop3_b32 v10, v3, v10, 1 bitop3:0x36
	v_bitop3_b32 v3, v3, v5, 1 bitop3:0x36
	v_lshlrev_b32_e32 v0, 4, v0
	s_lshl_b32 s18, s3, 5
	s_ashr_i32 s31, s2, 7
	s_lshl_b32 s2, s3, 13
	v_sub_u32_e32 v29, v29, v154
	v_and_b32_e32 v2, 0x300, v2
	v_and_b32_e32 v6, 12, v6
	v_bfe_u32 v8, v155, 4, 2
	v_and_b32_e32 v9, 12, v9
	v_lshlrev_b32_e32 v176, 4, v10
	v_bitop3_b32 v10, v38, v5, v37 bitop3:0x36
	v_lshlrev_b32_e32 v178, 4, v3
	v_lshl_add_u32 v3, v148, 11, 0
	v_and_b32_e32 v21, 0xf0, v0
	s_add_i32 s30, s18, 0x8000
	s_and_b32 s52, s18, 32
	v_lshlrev_b32_e32 v0, 4, v148
	s_add_i32 s2, s2, 0
	v_readlane_b32 s18, v254, 56
	v_add_u32_e32 v29, 0x1ff, v29
	v_or_b32_e32 v151, 4, v148
	v_or_b32_e32 v153, 8, v148
	v_or_b32_e32 v157, 12, v148
	v_bitop3_b32 v6, v6, v140, v148 bitop3:0x36
	v_bitop3_b32 v8, v9, v140, v8 bitop3:0x36
	v_lshlrev_b32_e32 v175, 4, v11
	v_lshlrev_b32_e32 v177, 4, v10
	v_or_b32_e32 v179, 16, v148
	v_or_b32_e32 v180, 20, v148
	v_or_b32_e32 v181, 24, v148
	v_or_b32_e32 v182, 28, v148
	v_add3_u32 v183, v3, v2, v36
	v_bitop3_b32 v2, v148, v154, 28 bitop3:0x36
	v_bitop3_b32 v3, v148, v154, 24 bitop3:0x36
	v_bitop3_b32 v5, v148, v154, 20 bitop3:0x36
	v_bitop3_b32 v10, v148, v154, 12 bitop3:0x36
	v_bitop3_b32 v11, v148, v154, 8 bitop3:0x36
	v_bitop3_b32 v12, v148, v154, 4 bitop3:0x36
	v_and_b32_e32 v4, 8, v4
	v_lshlrev_b32_e32 v22, 8, v140
	v_lshl_add_u64 v[132:133], s[16:17], 0, v[0:1]
	s_add_i32 s2, s2, 0x11200
	v_lshlrev_b32_e32 v0, 4, v140
	v_readlane_b32 s19, v254, 57
	v_lshrrev_b32_e32 v30, 9, v29
	v_lshlrev_b32_e32 v160, 4, v6
	v_lshlrev_b32_e32 v161, 4, v8
	v_lshlrev_b32_e32 v2, 4, v2
	v_lshlrev_b32_e32 v3, 4, v3
	v_lshlrev_b32_e32 v5, 4, v5
	v_lshlrev_b32_e32 v10, 4, v10
	v_lshlrev_b32_e32 v11, 4, v11
	v_lshlrev_b32_e32 v12, 4, v12
	v_bitop3_b32 v14, v13, v140, 14 bitop3:0x36
	v_bitop3_b32 v15, v13, v140, 12 bitop3:0x36
	v_bitop3_b32 v16, v13, v140, 10 bitop3:0x36
	v_bitop3_b32 v17, v13, v140, 8 bitop3:0x36
	v_bitop3_b32 v18, v13, v140, 6 bitop3:0x36
	v_bitop3_b32 v19, v13, v140, 4 bitop3:0x36
	v_bitop3_b32 v20, v13, v140, 2 bitop3:0x36
	v_xor_b32_e32 v13, v13, v140
	v_add3_u32 v4, s2, v22, v4
	v_lshl_add_u64 v[134:135], s[18:19], 0, v[0:1]
	v_lshl_add_u32 v22, v148, 8, s2
	v_lshl_add_u64 v[136:137], s[16:17], 0, v[0:1]
	v_lshl_add_u32 v0, v151, 8, s2
	v_lshl_add_u32 v23, v153, 8, s2
	v_lshl_add_u32 v24, v157, 8, s2
	v_lshl_add_u32 v25, v179, 8, s2
	v_lshl_add_u32 v26, v180, 8, s2
	v_lshl_add_u32 v27, v181, 8, s2
	v_lshl_add_u32 v28, v182, 8, s2
	v_add_u32_e32 v30, 1, v30
	s_movk_i32 s2, 0x1ff
	s_movk_i32 s0, 0x1d0
	v_lshlrev_b32_e32 v159, 3, v148
	v_add_u32_e32 v6, 0, v160
	v_add_u32_e32 v7, 0, v145
	v_add_u32_e32 v8, 0, v161
	v_add_u32_e32 v9, 0, v147
	v_and_b32_e32 v2, 0xf0, v2
	v_and_b32_e32 v3, 0xf0, v3
	v_and_b32_e32 v5, 0xf0, v5
	v_and_b32_e32 v10, 0xf0, v10
	v_and_b32_e32 v11, 0xf0, v11
	v_and_b32_e32 v12, 0xf0, v12
	v_lshlrev_b32_e32 v14, 4, v14
	v_lshlrev_b32_e32 v15, 4, v15
	v_lshlrev_b32_e32 v16, 4, v16
	v_lshlrev_b32_e32 v17, 4, v17
	v_lshlrev_b32_e32 v18, 4, v18
	v_lshlrev_b32_e32 v19, 4, v19
	v_lshlrev_b32_e32 v20, 4, v20
	v_lshlrev_b32_e32 v13, 4, v13
	v_cmp_lt_u32_e64 s[36:37], s2, v29
	v_and_b32_e32 v184, 0xfffffe, v30
	v_readlane_b32 s2, v253, 48
	v_cmp_lt_i32_e64 s[0:1], s0, v154
	v_or_b32_e32 v162, 0x80, v159
	v_lshl_add_u32 v185, v184, 9, v154
	v_cmp_ne_u32_e64 s[38:39], v30, v184
	v_add_u32_e32 v186, s2, v141
	v_add_u32_e32 v187, v6, v144
	v_add_u32_e32 v188, v7, v144
	v_add_u32_e32 v189, v8, v146
	v_add_u32_e32 v190, v9, v146
	v_add_u32_e32 v191, v4, v13
	v_add_u32_e32 v192, v4, v20
	v_add_u32_e32 v193, v4, v19
	v_add_u32_e32 v194, v4, v18
	v_add_u32_e32 v195, v4, v17
	v_add_u32_e32 v196, v4, v16
	v_add_u32_e32 v197, v4, v15
	v_add_u32_e32 v198, v4, v14
	v_add_u32_e32 v199, v22, v21
	v_add_u32_e32 v200, v0, v12
	v_add_u32_e32 v201, v23, v11
	v_add_u32_e32 v202, v24, v10
	v_add_u32_e32 v203, v25, v21
	v_add_u32_e32 v204, v26, v5
	v_add_u32_e32 v205, v27, v3
	v_add_u32_e32 v223, v28, v2
	s_mov_b32 s2, s84
	v_writelane_b32 v255, s2, 0
	s_and_b32 s3, s2, 7
	s_lshl_b32 s3, s3, 5
	s_bfe_u32 s53, s2, 0x50003
	s_or_b32 s3, s3, s53
	s_and_b32 s53, s2, 0xffffff00
	s_or_b32 s3, s3, s53
	s_cmpk_lt_u32 s2, 0x600
	s_cselect_b32 s53, s3, s2
	s_mov_b32 s96, s94
	s_branch .LBB0_258

.LBB0_257:
	v_sub_f32_e32 v3, v224, v236
	v_min_f32_e32 v3, 0x42fc0000, v3
	s_mov_b32 s3, 0xc2fc0000
	v_cmp_gt_f32_e32 vcc, s3, v3
	v_mov_b32_e32 v0, v121
	s_nop 1
	v_permlane16_swap_b32_e32 v121, v0
	v_cndmask_b32_e32 v68, 0, v219, vcc
	v_add_f32_e32 v3, v3, v68
	v_add_f32_e32 v0, v121, v0
	v_exp_f32_e32 v3, v3
	v_mov_b32_e32 v2, v0
	s_nop 1
	v_permlane32_swap_b32_e32 v0, v2
	v_add_f32_e32 v0, v0, v2
	v_cndmask_b32_e32 v2, 0, v220, vcc
	v_ldexp_f32 v2, v3, v2
	v_add_f32_e32 v2, v2, v0
	v_cndmask_b32_e64 v0, v0, v2, s[18:19]
	v_div_scale_f32 v2, s[26:27], v0, v0, 1.0
	v_rcp_f32_e32 v3, v2
	s_nop 0
	v_fma_f32 v68, -v2, v3, 1.0
	v_fmac_f32_e32 v3, v68, v3
	v_div_scale_f32 v68, vcc, 1.0, v0, 1.0
	v_mul_f32_e32 v69, v68, v3
	v_fma_f32 v70, -v2, v69, v68
	v_fmac_f32_e32 v69, v70, v3
	v_fma_f32 v2, -v2, v69, v68
	v_div_fmas_f32 v2, v2, v3, v69
	v_div_fixup_f32 v0, v2, v0, 1.0
	v_mul_f32_e32 v2, v64, v0
	v_mul_f32_e32 v3, v65, v0
	v_cvt_pk_bf16_f32 v2, v2, v3
	v_mul_f32_e32 v3, v66, v0
	v_mul_f32_e32 v64, v67, v0
	v_cvt_pk_bf16_f32 v3, v3, v64
	ds_write_b64 v191, v[2:3]
	v_mul_f32_e32 v2, v60, v0
	v_mul_f32_e32 v3, v61, v0
	v_cvt_pk_bf16_f32 v2, v2, v3
	v_mul_f32_e32 v3, v62, v0
	v_mul_f32_e32 v60, v63, v0
	v_cvt_pk_bf16_f32 v3, v3, v60
	ds_write_b64 v192, v[2:3]
	v_mul_f32_e32 v2, v56, v0
	v_mul_f32_e32 v3, v57, v0
	v_cvt_pk_bf16_f32 v2, v2, v3
	v_mul_f32_e32 v3, v58, v0
	v_mul_f32_e32 v56, v59, v0
	v_cvt_pk_bf16_f32 v3, v3, v56
	ds_write_b64 v193, v[2:3]
	v_mul_f32_e32 v2, v52, v0
	v_mul_f32_e32 v3, v53, v0
	v_cvt_pk_bf16_f32 v2, v2, v3
	v_mul_f32_e32 v3, v54, v0
	v_mul_f32_e32 v52, v55, v0
	v_cvt_pk_bf16_f32 v3, v3, v52
	ds_write_b64 v194, v[2:3]
	v_mul_f32_e32 v2, v48, v0
	v_mul_f32_e32 v3, v49, v0
	v_cvt_pk_bf16_f32 v2, v2, v3
	v_mul_f32_e32 v3, v50, v0
	v_mul_f32_e32 v48, v51, v0
	v_cvt_pk_bf16_f32 v3, v3, v48
	ds_write_b64 v195, v[2:3]
	v_mul_f32_e32 v2, v44, v0
	v_mul_f32_e32 v3, v45, v0
	v_cvt_pk_bf16_f32 v2, v2, v3
	v_mul_f32_e32 v3, v46, v0
	v_mul_f32_e32 v44, v47, v0
	v_cvt_pk_bf16_f32 v3, v3, v44
	ds_write_b64 v196, v[2:3]
	v_mul_f32_e32 v2, v40, v0
	v_mul_f32_e32 v3, v41, v0
	v_cvt_pk_bf16_f32 v2, v2, v3
	v_mul_f32_e32 v3, v42, v0
	v_mul_f32_e32 v40, v43, v0
	v_cvt_pk_bf16_f32 v3, v3, v40
	ds_write_b64 v197, v[2:3]
	v_mul_f32_e32 v2, v36, v0
	v_mul_f32_e32 v3, v37, v0
	v_cvt_pk_bf16_f32 v2, v2, v3
	v_mul_f32_e32 v3, v38, v0
	v_sub_f32_e32 v38, v224, v128
	v_min_f32_e32 v38, 0x42fc0000, v38
	v_cmp_gt_f32_e32 vcc, s3, v38
	v_mov_b32_e32 v36, v120
	s_nop 1
	v_permlane16_swap_b32_e32 v120, v36
	v_cndmask_b32_e32 v40, 0, v219, vcc
	v_add_f32_e32 v38, v38, v40
	v_add_f32_e32 v36, v120, v36
	v_exp_f32_e32 v38, v38
	v_mov_b32_e32 v37, v36
	s_nop 1
	v_permlane32_swap_b32_e32 v36, v37
	v_add_f32_e32 v36, v36, v37
	v_cndmask_b32_e32 v37, 0, v220, vcc
	v_ldexp_f32 v37, v38, v37
	v_add_f32_e32 v37, v37, v36
	v_cndmask_b32_e64 v36, v36, v37, s[18:19]
	v_div_scale_f32 v37, s[18:19], v36, v36, 1.0
	v_rcp_f32_e32 v38, v37
	v_mul_f32_e32 v0, v39, v0
	v_cvt_pk_bf16_f32 v3, v3, v0
	ds_write_b64 v198, v[2:3]
	v_fma_f32 v0, -v37, v38, 1.0
	v_fmac_f32_e32 v38, v0, v38
	v_div_scale_f32 v0, vcc, 1.0, v36, 1.0
	v_mul_f32_e32 v2, v0, v38
	v_fma_f32 v3, -v37, v2, v0
	v_fmac_f32_e32 v2, v3, v38
	v_fma_f32 v0, -v37, v2, v0
	v_div_fmas_f32 v0, v0, v38, v2
	v_div_fixup_f32 v0, v0, v36, 1.0
	v_mul_f32_e32 v2, v32, v0
	v_mul_f32_e32 v3, v33, v0
	v_cvt_pk_bf16_f32 v2, v2, v3
	v_mul_f32_e32 v3, v34, v0
	v_mul_f32_e32 v32, v35, v0
	v_cvt_pk_bf16_f32 v3, v3, v32
	ds_write_b64 v191, v[2:3] offset:4096
	v_mul_f32_e32 v2, v28, v0
	v_mul_f32_e32 v3, v29, v0
	v_cvt_pk_bf16_f32 v2, v2, v3
	v_mul_f32_e32 v3, v30, v0
	v_mul_f32_e32 v28, v31, v0
	v_cvt_pk_bf16_f32 v3, v3, v28
	ds_write_b64 v192, v[2:3] offset:4096
	v_mul_f32_e32 v2, v24, v0
	v_mul_f32_e32 v3, v25, v0
	v_cvt_pk_bf16_f32 v2, v2, v3
	v_mul_f32_e32 v3, v26, v0
	v_mul_f32_e32 v24, v27, v0
	v_cvt_pk_bf16_f32 v3, v3, v24
	ds_write_b64 v193, v[2:3] offset:4096
	v_mul_f32_e32 v2, v20, v0
	v_mul_f32_e32 v3, v21, v0
	v_cvt_pk_bf16_f32 v2, v2, v3
	v_mul_f32_e32 v3, v22, v0
	v_mul_f32_e32 v20, v23, v0
	v_cvt_pk_bf16_f32 v3, v3, v20
	ds_write_b64 v194, v[2:3] offset:4096
	v_mul_f32_e32 v2, v16, v0
	v_mul_f32_e32 v3, v17, v0
	v_cvt_pk_bf16_f32 v2, v2, v3
	v_mul_f32_e32 v3, v18, v0
	v_mul_f32_e32 v16, v19, v0
	v_cvt_pk_bf16_f32 v3, v3, v16
	ds_write_b64 v195, v[2:3] offset:4096
	v_mul_f32_e32 v2, v12, v0
	v_mul_f32_e32 v3, v13, v0
	v_cvt_pk_bf16_f32 v2, v2, v3
	v_mul_f32_e32 v3, v14, v0
	v_mul_f32_e32 v12, v15, v0
	v_cvt_pk_bf16_f32 v3, v3, v12
	ds_write_b64 v196, v[2:3] offset:4096
	v_mul_f32_e32 v2, v8, v0
	v_mul_f32_e32 v3, v9, v0
	v_cvt_pk_bf16_f32 v2, v2, v3
	v_mul_f32_e32 v3, v10, v0
	v_mul_f32_e32 v8, v11, v0
	v_cvt_pk_bf16_f32 v3, v3, v8
	ds_write_b64 v197, v[2:3] offset:4096
	v_mul_f32_e32 v2, v4, v0
	v_mul_f32_e32 v3, v5, v0
	v_cvt_pk_bf16_f32 v2, v2, v3
	v_mul_f32_e32 v3, v6, v0
	v_mul_f32_e32 v0, v7, v0
	v_cvt_pk_bf16_f32 v3, v3, v0
	ds_write_b64 v198, v[2:3] offset:4096
	ds_read_b128 v[2:5], v199
	v_add_u32_e32 v6, s56, v148
	s_ashr_i32 s3, s2, 31
	v_ashrrev_i32_e32 v7, 31, v6
	v_lshl_add_u64 v[10:11], s[2:3], 1, v[134:135]
	v_lshlrev_b64 v[6:7], 12, v[6:7]
	v_lshl_add_u64 v[12:13], v[10:11], 0, v[6:7]
	ds_read_b128 v[6:9], v200
	s_waitcnt lgkmcnt(1)
	global_store_dwordx4 v[12:13], v[2:5], off
	s_nop 1
	v_add_u32_e32 v2, s56, v151
	v_ashrrev_i32_e32 v3, 31, v2
	v_lshlrev_b64 v[2:3], 12, v[2:3]
	v_lshl_add_u64 v[2:3], v[10:11], 0, v[2:3]
	s_waitcnt lgkmcnt(0)
	global_store_dwordx4 v[2:3], v[6:9], off
	ds_read_b128 v[2:5], v201
	s_nop 0
	v_add_u32_e32 v6, s56, v153
	v_ashrrev_i32_e32 v7, 31, v6
	v_lshlrev_b64 v[6:7], 12, v[6:7]
	v_lshl_add_u64 v[12:13], v[10:11], 0, v[6:7]
	ds_read_b128 v[6:9], v202
	s_waitcnt lgkmcnt(1)
	global_store_dwordx4 v[12:13], v[2:5], off
	s_nop 1
	v_add_u32_e32 v2, s56, v157
	v_ashrrev_i32_e32 v3, 31, v2
	v_lshlrev_b64 v[2:3], 12, v[2:3]
	v_lshl_add_u64 v[2:3], v[10:11], 0, v[2:3]
	s_waitcnt lgkmcnt(0)
	global_store_dwordx4 v[2:3], v[6:9], off
	ds_read_b128 v[2:5], v203
	s_nop 0
	v_add_u32_e32 v6, s56, v179
	v_ashrrev_i32_e32 v7, 31, v6
	v_lshlrev_b64 v[6:7], 12, v[6:7]
	v_lshl_add_u64 v[12:13], v[10:11], 0, v[6:7]
	ds_read_b128 v[6:9], v204
	s_waitcnt lgkmcnt(1)
	global_store_dwordx4 v[12:13], v[2:5], off
	s_nop 1
	v_add_u32_e32 v2, s56, v180
	v_ashrrev_i32_e32 v3, 31, v2
	v_lshlrev_b64 v[2:3], 12, v[2:3]
	v_lshl_add_u64 v[2:3], v[10:11], 0, v[2:3]
	s_waitcnt lgkmcnt(0)
	global_store_dwordx4 v[2:3], v[6:9], off
	ds_read_b128 v[2:5], v205
	s_nop 0
	v_add_u32_e32 v6, s56, v181
	v_ashrrev_i32_e32 v7, 31, v6
	v_lshlrev_b64 v[6:7], 12, v[6:7]
	v_lshl_add_u64 v[12:13], v[10:11], 0, v[6:7]
	ds_read_b128 v[6:9], v223
	s_waitcnt lgkmcnt(1)
	global_store_dwordx4 v[12:13], v[2:5], off
	s_nop 1
	v_add_u32_e32 v2, s56, v182
	v_ashrrev_i32_e32 v3, 31, v2
	v_lshlrev_b64 v[2:3], 12, v[2:3]
	v_lshl_add_u64 v[2:3], v[10:11], 0, v[2:3]
	s_waitcnt lgkmcnt(0)
	global_store_dwordx4 v[2:3], v[6:9], off
	s_load_dword s2, s[98:99], 0x10
	s_waitcnt lgkmcnt(0)
	s_lshr_b32 s2, s2, 16
	s_cmp_lg_u32 s2, 0
	s_cselect_b64 s[2:3], -1, 0
	s_cmp_lg_u64 s[2:3], 0
	v_readlane_b32 s2, v255, 0
	s_nop 1
	s_addc_u32 s2, s2, s28
	v_writelane_b32 v255, s2, 0
	s_cmp_ge_i32 s2, s6
	s_cbranch_scc1 .LBB0_352
	s_and_b32 s3, s2, 7
	s_lshl_b32 s3, s3, 5
	s_bfe_u32 s53, s2, 0x50003
	s_or_b32 s3, s3, s53
	s_and_b32 s53, s2, 0xffffff00
	s_or_b32 s3, s3, s53
	s_cmpk_lt_u32 s2, 0x600
	s_cselect_b32 s53, s3, s2

	.amdhsa_kernel _Z6mk_fwd1P
		.amdhsa_group_segment_fixed_size 0
		.amdhsa_private_segment_fixed_size 0
		.amdhsa_kernarg_size 448
		.amdhsa_user_sgpr_count 2
		.amdhsa_user_sgpr_dispatch_ptr 0
		.amdhsa_user_sgpr_queue_ptr 0
		.amdhsa_user_sgpr_kernarg_segment_ptr 1
		.amdhsa_user_sgpr_dispatch_id 0
		.amdhsa_user_sgpr_kernarg_preload_length 0
		.amdhsa_user_sgpr_kernarg_preload_offset 0
		.amdhsa_user_sgpr_private_segment_size 0
		.amdhsa_uses_dynamic_stack 0
		.amdhsa_enable_private_segment 0
		.amdhsa_system_sgpr_workgroup_id_x 1
		.amdhsa_system_sgpr_workgroup_id_y 0
		.amdhsa_system_sgpr_workgroup_id_z 0
		.amdhsa_system_sgpr_workgroup_info 0
		.amdhsa_system_vgpr_workitem_id 2
		.amdhsa_next_free_vgpr 256
		.amdhsa_next_free_sgpr 100
		.amdhsa_accum_offset 256
		.amdhsa_reserve_vcc 1
		.amdhsa_float_round_mode_32 0
		.amdhsa_float_round_mode_16_64 0
		.amdhsa_float_denorm_mode_32 3
		.amdhsa_float_denorm_mode_16_64 3
		.amdhsa_dx10_clamp 1
		.amdhsa_ieee_mode 1
		.amdhsa_fp16_overflow 0
		.amdhsa_tg_split 0
		.amdhsa_exception_fp_ieee_invalid_op 0
		.amdhsa_exception_fp_denorm_src 0
		.amdhsa_exception_fp_ieee_div_zero 0
		.amdhsa_exception_fp_ieee_overflow 0
		.amdhsa_exception_fp_ieee_underflow 0
		.amdhsa_exception_fp_ieee_inexact 0
		.amdhsa_exception_int_div_zero 0
	.end_amdhsa_kernel

amdhsa.kernels:
  - .agpr_count:     0
    .args:
      - .offset:         0
        .size:           192
        .value_kind:     by_value
      - .offset:         192
        .size:           4
        .value_kind:     hidden_block_count_x
      - .offset:         196
        .size:           4
        .value_kind:     hidden_block_count_y
      - .offset:         200
        .size:           4
        .value_kind:     hidden_block_count_z
      - .offset:         204
        .size:           2
        .value_kind:     hidden_group_size_x
      - .offset:         206
        .size:           2
        .value_kind:     hidden_group_size_y
      - .offset:         208
        .size:           2
        .value_kind:     hidden_group_size_z
      - .offset:         210
        .size:           2
        .value_kind:     hidden_remainder_x
      - .offset:         212
        .size:           2
        .value_kind:     hidden_remainder_y
      - .offset:         214
        .size:           2
        .value_kind:     hidden_remainder_z
      - .offset:         232
        .size:           8
        .value_kind:     hidden_global_offset_x
      - .offset:         240
        .size:           8
        .value_kind:     hidden_global_offset_y
      - .offset:         248
        .size:           8
        .value_kind:     hidden_global_offset_z
      - .offset:         256
        .size:           2
        .value_kind:     hidden_grid_dims
      - .offset:         280
        .size:           8
        .value_kind:     hidden_multigrid_sync_arg
      - .offset:         312
        .size:           4
        .value_kind:     hidden_dynamic_lds_size
    .group_segment_fixed_size: 0
    .kernarg_segment_align: 8
    .kernarg_segment_size: 448
    .language:       OpenCL C
    .language_version:
      - 2
      - 0
    .max_flat_workgroup_size: 512
    .name:           _Z6mk_fwd1P
    .private_segment_fixed_size: 0
    .sgpr_count:     106
    .sgpr_spill_count: 206
    .symbol:         _Z6mk_fwd1P.kd
    .uniform_work_group_size: 1
    .uses_dynamic_stack: false
    .vgpr_count:     256
    .vgpr_spill_count: 0
    .wavefront_size: 64
